# P0 absmax job moved from workgroup 0 to workgroup 255 (lighter item mix); ATTB table init: unneeded early vmcnt(0) in front of the table address removed; on top of v91
# speedup vs baseline: 1.0011x; 1.0011x over previous
; #define LAS __attribute__((address_space(3)))
; __device__ __forceinline__ float wg_absmax(const float* p, int n, LAS float* scr, int tid) {
;     float m = 0.f;
;     for (int i = tid; i < n; i += NWAVES * 64) m = fmaxf(m, fabsf(p[i]));
; __global__ void __launch_bounds__(NWAVES * 64, 2) fwd_kernel(Args args) {
;     ...
;         if (blockIdx.x == 0) {
;             LAS float* scr0 = (LAS float*)(F.lds + RING_OFF + 8 * 16384);
;             const float ca = 64.0f * QSCALE * att::wg_absmax(args.in[4], 192, scr0, F.tid) * att::wg_absmax(args.in[5], 192, scr0, F.tid) + LOG2E * att::wg_absmax(args.in[6], 48 * 32, scr0, F.tid);
;             const float cb = 64.0f * QSCALE * att::wg_absmax(args.in[9], 64, scr0, F.tid) * att::wg_absmax(args.in[10], 64, scr0, F.tid) + LOG2E * att::wg_absmax(args.in[11], NH * 15 * 31, scr0, F.tid);
.LBB0_61:
	s_cmpk_eq_u32 s87, 0xff
	s_cbranch_scc1 .LBB0_63
	s_cmp_lt_i32 s67, 2
	s_cbranch_scc0 .LBB0_138
	s_branch .LBB0_185
.LBB0_63:
	v_readlane_b32 s8, v253, 8
	v_readlane_b32 s9, v253, 9
	v_readlane_b32 s10, v253, 10
	v_readlane_b32 s11, v253, 11
	v_readlane_b32 s12, v253, 12
	v_readlane_b32 s13, v253, 13
	v_mov_b32_e32 v0, 0
	v_mov_b32_e32 v1, 0
	v_mov_b32_e32 v2, 0
	v_mov_b32_e32 v3, 0
	v_mov_b32_e32 v4, 0
	v_mov_b32_e32 v5, 0
	v_mov_b32_e32 v6, 0
	v_mov_b32_e32 v7, 0
	v_mov_b32_e32 v8, 0
	v_mov_b32_e32 v9, 0
	v_mov_b32_e32 v10, 0
	v_mov_b32_e32 v11, 0
	v_mov_b32_e32 v12, 0
	v_mov_b32_e32 v13, 0
	v_mov_b32_e32 v14, 0
	v_mov_b32_e32 v15, 0
	v_mov_b32_e32 v16, 0
	v_mov_b32_e32 v17, 0
	v_mov_b32_e32 v18, 0
	v_mov_b32_e32 v19, 0
	v_mov_b32_e32 v20, 0
	v_mov_b32_e32 v21, 0
	v_lshlrev_b32_e32 v22, 2, v64
	v_cmp_gt_u32_e32 vcc, 0xc0, v64
	s_and_saveexec_b64 s[0:1], vcc
	global_load_dword v0, v22, s[52:53]
	global_load_dword v1, v22, s[54:55]
	s_mov_b64 exec, s[0:1]
	global_load_dword v2, v22, s[56:57]
	global_load_dword v3, v22, s[56:57] offset:2048
	v_add_u32_e32 v23, 0x1000, v22
	global_load_dword v4, v23, s[56:57]
	v_cmp_gt_u32_e32 vcc, 64, v64
	s_and_saveexec_b64 s[0:1], vcc
	global_load_dword v5, v22, s[8:9]
	global_load_dword v6, v22, s[10:11]
	s_mov_b64 exec, s[0:1]
	v_mov_b32_e32 v23, v22
	global_load_dword v7, v23, s[12:13]
	global_load_dword v8, v23, s[12:13] offset:2048
	v_add_u32_e32 v23, 0x1000, v23
	global_load_dword v9, v23, s[12:13]
	global_load_dword v10, v23, s[12:13] offset:2048
	v_add_u32_e32 v23, 0x1000, v23
	global_load_dword v11, v23, s[12:13]
	global_load_dword v12, v23, s[12:13] offset:2048
	v_add_u32_e32 v23, 0x1000, v23
	global_load_dword v13, v23, s[12:13]
	global_load_dword v14, v23, s[12:13] offset:2048
	v_add_u32_e32 v23, 0x1000, v23
	global_load_dword v15, v23, s[12:13]
	global_load_dword v16, v23, s[12:13] offset:2048
	v_add_u32_e32 v23, 0x1000, v23
	global_load_dword v17, v23, s[12:13]
	global_load_dword v18, v23, s[12:13] offset:2048
	v_add_u32_e32 v23, 0x1000, v23
	global_load_dword v19, v23, s[12:13]
	global_load_dword v20, v23, s[12:13] offset:2048
	v_add_u32_e32 v23, 0x1000, v23
	v_cmp_gt_u32_e32 vcc, 0x110, v64
	s_and_saveexec_b64 s[0:1], vcc
	global_load_dword v21, v23, s[12:13]
	s_mov_b64 exec, s[0:1]
	s_waitcnt vmcnt(0)
; __device__ __forceinline__ float wave_max(float v) { v = fmaxf(v, dpp_mov<0xB1>(v)); v = fmaxf(v, dpp_mov<0x4E>(v)); v = fmaxf(v, dpp_mov<0x141>(v)); v = fmaxf(v, dpp_mov<0x140>(v)); v = max_x16(v); return max_x32(v); }
; #define LAS __attribute__((address_space(3)))
; __device__ __forceinline__ float wg_absmax(const float* p, int n, LAS float* scr, int tid) {
;     float m = 0.f;
;     for (int i = tid; i < n; i += NWAVES * 64) m = fmaxf(m, fabsf(p[i]));
;     m = wave_max(m);
;     __syncthreads();
;     if ((tid & 63) == 0) scr[tid >> 6] = m;
;     __syncthreads();
;     float r = scr[0];
; #pragma unroll
;     for (int i = 1; i < NWAVES; ++i) r = fmaxf(r, scr[i]);
;     return r;
; __global__ void __launch_bounds__(NWAVES * 64, 2) fwd_kernel(Args args) {
;     ...
;             const float ca = 64.0f * QSCALE * att::wg_absmax(args.in[4], 192, scr0, F.tid) * att::wg_absmax(args.in[5], 192, scr0, F.tid) + LOG2E * att::wg_absmax(args.in[6], 48 * 32, scr0, F.tid);
;             const float cb = 64.0f * QSCALE * att::wg_absmax(args.in[9], 64, scr0, F.tid) * att::wg_absmax(args.in[10], 64, scr0, F.tid) + LOG2E * att::wg_absmax(args.in[11], NH * 15 * 31, scr0, F.tid);
;             if (F.tid == 0) { float* cs = (float*)(ws + WS_CSHIFT); cs[0] = ca; cs[1] = cb; }
	v_max_f32_e64 v24, |v0|, |v0|
	v_max_f32_e64 v25, |v1|, |v1|
	v_max_f32_e64 v26, |v2|, |v3|
	v_max_f32_e64 v27, |v5|, |v5|
	v_max_f32_e64 v28, |v6|, |v6|
	v_max_f32_e64 v29, |v7|, |v8|
	v_max_f32_e64 v26, v26, |v4|
	v_max_f32_e64 v29, v29, |v9|
	v_max_f32_e64 v29, v29, |v10|
	v_max_f32_e64 v29, v29, |v11|
	v_max_f32_e64 v29, v29, |v12|
	v_max_f32_e64 v29, v29, |v13|
	v_max_f32_e64 v29, v29, |v14|
	v_max_f32_e64 v29, v29, |v15|
	v_max_f32_e64 v29, v29, |v16|
	v_max_f32_e64 v29, v29, |v17|
	v_max_f32_e64 v29, v29, |v18|
	v_max_f32_e64 v29, v29, |v19|
	v_max_f32_e64 v29, v29, |v20|
	v_max_f32_e64 v29, v29, |v21|
	s_nop 1
	v_mov_b32_dpp v30, v24 quad_perm:[1,0,3,2] row_mask:0xf bank_mask:0xf bound_ctrl:1
	v_mov_b32_dpp v31, v25 quad_perm:[1,0,3,2] row_mask:0xf bank_mask:0xf bound_ctrl:1
	v_mov_b32_dpp v32, v26 quad_perm:[1,0,3,2] row_mask:0xf bank_mask:0xf bound_ctrl:1
	v_mov_b32_dpp v33, v27 quad_perm:[1,0,3,2] row_mask:0xf bank_mask:0xf bound_ctrl:1
	v_mov_b32_dpp v34, v28 quad_perm:[1,0,3,2] row_mask:0xf bank_mask:0xf bound_ctrl:1
	v_mov_b32_dpp v35, v29 quad_perm:[1,0,3,2] row_mask:0xf bank_mask:0xf bound_ctrl:1
	v_max_f32_e32 v24, v24, v30
	v_max_f32_e32 v25, v25, v31
	v_max_f32_e32 v26, v26, v32
	v_max_f32_e32 v27, v27, v33
	v_max_f32_e32 v28, v28, v34
	v_max_f32_e32 v29, v29, v35
	s_nop 1
	v_mov_b32_dpp v30, v24 quad_perm:[2,3,0,1] row_mask:0xf bank_mask:0xf bound_ctrl:1
	v_mov_b32_dpp v31, v25 quad_perm:[2,3,0,1] row_mask:0xf bank_mask:0xf bound_ctrl:1
	v_mov_b32_dpp v32, v26 quad_perm:[2,3,0,1] row_mask:0xf bank_mask:0xf bound_ctrl:1
	v_mov_b32_dpp v33, v27 quad_perm:[2,3,0,1] row_mask:0xf bank_mask:0xf bound_ctrl:1
	v_mov_b32_dpp v34, v28 quad_perm:[2,3,0,1] row_mask:0xf bank_mask:0xf bound_ctrl:1
	v_mov_b32_dpp v35, v29 quad_perm:[2,3,0,1] row_mask:0xf bank_mask:0xf bound_ctrl:1
	v_max_f32_e32 v24, v24, v30
	v_max_f32_e32 v25, v25, v31
	v_max_f32_e32 v26, v26, v32
	v_max_f32_e32 v27, v27, v33
	v_max_f32_e32 v28, v28, v34
	v_max_f32_e32 v29, v29, v35
	s_nop 1
	v_mov_b32_dpp v30, v24 row_half_mirror row_mask:0xf bank_mask:0xf bound_ctrl:1
	v_mov_b32_dpp v31, v25 row_half_mirror row_mask:0xf bank_mask:0xf bound_ctrl:1
	v_mov_b32_dpp v32, v26 row_half_mirror row_mask:0xf bank_mask:0xf bound_ctrl:1
	v_mov_b32_dpp v33, v27 row_half_mirror row_mask:0xf bank_mask:0xf bound_ctrl:1
	v_mov_b32_dpp v34, v28 row_half_mirror row_mask:0xf bank_mask:0xf bound_ctrl:1
	v_mov_b32_dpp v35, v29 row_half_mirror row_mask:0xf bank_mask:0xf bound_ctrl:1
	v_max_f32_e32 v24, v24, v30
	v_max_f32_e32 v25, v25, v31
	v_max_f32_e32 v26, v26, v32
	v_max_f32_e32 v27, v27, v33
	v_max_f32_e32 v28, v28, v34
	v_max_f32_e32 v29, v29, v35
	s_nop 1
	v_mov_b32_dpp v30, v24 row_mirror row_mask:0xf bank_mask:0xf bound_ctrl:1
	v_mov_b32_dpp v31, v25 row_mirror row_mask:0xf bank_mask:0xf bound_ctrl:1
	v_mov_b32_dpp v32, v26 row_mirror row_mask:0xf bank_mask:0xf bound_ctrl:1
	v_mov_b32_dpp v33, v27 row_mirror row_mask:0xf bank_mask:0xf bound_ctrl:1
	v_mov_b32_dpp v34, v28 row_mirror row_mask:0xf bank_mask:0xf bound_ctrl:1
	v_mov_b32_dpp v35, v29 row_mirror row_mask:0xf bank_mask:0xf bound_ctrl:1
	v_max_f32_e32 v24, v24, v30
	v_max_f32_e32 v25, v25, v31
	v_max_f32_e32 v26, v26, v32
	v_max_f32_e32 v27, v27, v33
	v_max_f32_e32 v28, v28, v34
	v_max_f32_e32 v29, v29, v35
	v_mov_b32_e32 v30, v24
	v_mov_b32_e32 v31, v25
	v_mov_b32_e32 v32, v26
	v_mov_b32_e32 v33, v27
	v_mov_b32_e32 v34, v28
	v_mov_b32_e32 v35, v29
	s_nop 1
	v_permlane16_swap_b32_e32 v24, v30
	v_permlane16_swap_b32_e32 v25, v31
	v_permlane16_swap_b32_e32 v26, v32
	v_permlane16_swap_b32_e32 v27, v33
	v_permlane16_swap_b32_e32 v28, v34
	v_permlane16_swap_b32_e32 v29, v35
	s_nop 1
	v_max_f32_e32 v24, v24, v30
	v_max_f32_e32 v25, v25, v31
	v_max_f32_e32 v26, v26, v32
	v_max_f32_e32 v27, v27, v33
	v_max_f32_e32 v28, v28, v34
	v_max_f32_e32 v29, v29, v35
	v_mov_b32_e32 v30, v24
	v_mov_b32_e32 v31, v25
	v_mov_b32_e32 v32, v26
	v_mov_b32_e32 v33, v27
	v_mov_b32_e32 v34, v28
	v_mov_b32_e32 v35, v29
	s_nop 1
	v_permlane32_swap_b32_e32 v24, v30
	v_permlane32_swap_b32_e32 v25, v31
	v_permlane32_swap_b32_e32 v26, v32
	v_permlane32_swap_b32_e32 v27, v33
	v_permlane32_swap_b32_e32 v28, v34
	v_permlane32_swap_b32_e32 v29, v35
	s_nop 1
	v_max_f32_e32 v24, v24, v30
	v_max_f32_e32 v25, v25, v31
	v_max_f32_e32 v26, v26, v32
	v_max_f32_e32 v27, v27, v33
	v_max_f32_e32 v28, v28, v34
	v_max_f32_e32 v29, v29, v35
	v_and_b32_e32 v36, 63, v64
	v_lshrrev_b32_e32 v37, 6, v64
	v_lshlrev_b32_e32 v37, 2, v37
	v_add_u32_e32 v37, 0x20000, v37
	v_cmp_eq_u32_e32 vcc, 0, v36
	s_and_saveexec_b64 s[0:1], vcc
	ds_write_b32 v37, v24
	ds_write_b32 v37, v25 offset:32
	ds_write_b32 v37, v26 offset:64
	ds_write_b32 v37, v27 offset:96
	ds_write_b32 v37, v28 offset:128
	ds_write_b32 v37, v29 offset:160
	s_mov_b64 exec, s[0:1]
	s_waitcnt lgkmcnt(0)
	s_barrier
	v_mov_b32_e32 v48, 0x20000
	ds_read_b128 v[0:3], v48
	ds_read_b128 v[4:7], v48 offset:16
	ds_read_b128 v[8:11], v48 offset:32
	ds_read_b128 v[12:15], v48 offset:48
	ds_read_b128 v[16:19], v48 offset:64
	ds_read_b128 v[20:23], v48 offset:80
	ds_read_b128 v[24:27], v48 offset:96
	ds_read_b128 v[28:31], v48 offset:112
	ds_read_b128 v[32:35], v48 offset:128
	ds_read_b128 v[36:39], v48 offset:144
	ds_read_b128 v[40:43], v48 offset:160
	ds_read_b128 v[44:47], v48 offset:176
	s_waitcnt lgkmcnt(0)
	v_max3_f32 v0, v0, v1, v2
	v_max3_f32 v4, v3, v4, v5
	v_max3_f32 v0, v0, v6, v7
	v_max_f32_e32 v0, v0, v4
	v_max3_f32 v8, v8, v9, v10
	v_max3_f32 v12, v11, v12, v13
	v_max3_f32 v8, v8, v14, v15
	v_max_f32_e32 v8, v8, v12
	v_max3_f32 v16, v16, v17, v18
	v_max3_f32 v20, v19, v20, v21
	v_max3_f32 v16, v16, v22, v23
	v_max_f32_e32 v16, v16, v20
	v_max3_f32 v24, v24, v25, v26
	v_max3_f32 v28, v27, v28, v29
	v_max3_f32 v24, v24, v30, v31
	v_max_f32_e32 v24, v24, v28
	v_max3_f32 v32, v32, v33, v34
	v_max3_f32 v36, v35, v36, v37
	v_max3_f32 v32, v32, v38, v39
	v_max_f32_e32 v32, v32, v36
	v_max3_f32 v40, v40, v41, v42
	v_max3_f32 v44, v43, v44, v45
	v_max3_f32 v40, v40, v46, v47
	v_max_f32_e32 v40, v40, v44
	v_mul_f32_e32 v0, 0x4138aa3b, v0
	v_mul_f32_e32 v24, 0x4138aa3b, v24
	v_mul_f32_e32 v16, 0x3fb8aa3b, v16
	v_mul_f32_e32 v40, 0x3fb8aa3b, v40
	v_fma_f32 v0, v0, v8, v16
	v_fma_f32 v1, v24, v32, v40
	v_readlane_b32 s4, v253, 20
	v_readlane_b32 s5, v253, 21
	v_mov_b32_e32 v2, 0
	v_cmp_eq_u32_e32 vcc, 0, v64
	s_and_saveexec_b64 s[0:1], vcc
	s_nop 3
	global_store_dwordx2 v2, v[0:1], s[4:5]

; #define LAS __attribute__((address_space(3)))
; __device__ __forceinline__ void tbl_b(int u, int tblbuf, const float* rpb, float cshift, LAS char* lds, int tid) {
;     const int h = (u >> 3) & 15;
;     for (int idx = tid; idx < 640; idx += NWAVES * 64) {
;         float v = NEG; const int e = idx - 16;
;         if (e >= 0 && e < 480 && (e & 31) < 31) v = LOG2E * rpb[(h * 15 + (e >> 5)) * 31 + (e & 31)] - cshift;
;         ((LAS float*)(lds + TBL_OFF + tblbuf * TBL_BYTES))[idx] = v;
;     }
.LBB0_633:
	v_add_u32_e32 v6, 0x1f0, v2
	v_cmp_gt_u32_e32 vcc, s13, v6
	s_and_b64 s[16:17], s[8:9], vcc
	v_mov_b32_e32 v5, 0xf149f2ca
	s_and_saveexec_b64 s[10:11], s[16:17]
	s_cbranch_execz .LBB0_632
	v_lshrrev_b32_e32 v5, 5, v6
	v_add_u32_e32 v5, s12, v5
	s_nop 0
	v_mad_u64_u32 v[6:7], s[16:17], v5, 31, v[144:145]
	v_readlane_b32 s16, v253, 6
	v_mov_b32_e32 v7, v4
	v_readlane_b32 s22, v253, 12
	v_readlane_b32 s23, v253, 13
	v_readlane_b32 s17, v253, 7
	v_readlane_b32 s18, v253, 8
	v_lshl_add_u64 v[6:7], v[6:7], 2, s[22:23]
	global_load_dword v5, v[6:7], off
	v_readlane_b32 s19, v253, 9
	v_readlane_b32 s20, v253, 10
	v_readlane_b32 s21, v253, 11
	s_waitcnt vmcnt(0)
	v_fma_f32 v5, v5, s14, -v145
	s_branch .LBB0_632
